# attention tile loop: the exp and P.V tail of a tile at priority 3 (QK and row max at 2, staging at 0)
# speedup vs baseline: 1.0036x; 1.0036x over previous
; __device__ __forceinline__ unsigned pk_bf16(float lo, float hi) { unsigned r; asm("v_cvt_pk_bf16_f32 %0, %1, %2" : "=v"(r) : "v"(lo), "v"(hi)); return r; }
; __device__ void attn_item(const Params& p, int s_idx, char* smem) {
;     ...
;             float mx = sv[0];
; #pragma unroll
;             for (int i = 1; i < 32; ++i) mx = fmaxf(mx, sv[i]);
;             mx = fmaxf(mx, __shfl_xor(mx, 32));
;             const float mnew = fmaxf(mrun, mx);
;             const float alpha = __builtin_amdgcn_exp2f(mrun - mnew);
;             mrun = mnew;
;             float psum = 0.f;
; #pragma unroll
;             for (int i = 0; i < 32; ++i) { sv[i] = __builtin_amdgcn_exp2f(sv[i] - mnew); psum += sv[i]; }
;             lsum = lsum * alpha + psum;
; #pragma unroll
;             for (int i = 0; i < 16; ++i) { O0[i] *= alpha; O1[i] *= alpha; }
; #pragma unroll
;             for (int g = 0; g < 4; ++g) {
;                 bf16x8 pf;
;                 {
;                     const unsigned u0 = pk_bf16(sv[g * 8 + 0], sv[g * 8 + 1]), u1 = pk_bf16(sv[g * 8 + 2], sv[g * 8 + 3]);
;                     const unsigned u2 = pk_bf16(sv[g * 8 + 4], sv[g * 8 + 5]), u3 = pk_bf16(sv[g * 8 + 6], sv[g * 8 + 7]);
;                     const uint4 uu = {u0, u1, u2, u3};
;                     pf = __builtin_bit_cast(bf16x8, uu);
;                 }
;                 const int koff = (g >> 1) * 32 + (g & 1) * 16 + 8 * hh;
;                 const bf16x8 v0 = *(const bf16x8*)(sVt + ql * 72 + koff);
;                 const bf16x8 v1 = *(const bf16x8*)(sVt + (32 + ql) * 72 + koff);
;                 O0 = __builtin_amdgcn_mfma_f32_32x32x16_bf16(v0, pf, O0, 0, 0, 0);
;                 O1 = __builtin_amdgcn_mfma_f32_32x32x16_bf16(v1, pf, O1, 0, 0, 0);
.LBB0_113:
	s_or_b64 exec, exec, s[42:43]
	v_max_f32_e32 v40, v123, v123
	v_max_f32_e32 v41, v122, v122
	v_max_f32_e32 v40, v41, v40
	v_max3_f32 v40, v40, v120, v121
	v_max3_f32 v40, v40, v118, v119
	v_max3_f32 v40, v40, v54, v55
	v_max3_f32 v40, v40, v116, v117
	v_max3_f32 v40, v40, v50, v51
	v_max3_f32 v40, v40, v124, v125
	v_max3_f32 v40, v40, v60, v61
	v_max3_f32 v40, v40, v58, v59
	v_max3_f32 v40, v40, v52, v53
	v_max3_f32 v40, v40, v56, v57
	v_max3_f32 v40, v40, v48, v49
	v_max3_f32 v40, v40, v38, v39
	v_max3_f32 v40, v40, v34, v35
	v_max3_f32 v40, v40, v36, v37
	v_max3_f32 v40, v40, v32, v33
	v_mov_b32_e32 v41, v40
	s_nop 1
	v_permlane32_swap_b32_e32 v41, v40
	s_waitcnt lgkmcnt(0)
	v_max_f32_e32 v42, v40, v41
	v_add_f32_e32 v43, 0xc3190000, v157
	v_cmp_lt_f32_e32 vcc, v42, v43
	s_andn2_b64 s[98:99], exec, vcc
	s_cbranch_scc0 .LBB0_114
	s_setprio 3
	v_cmp_gt_f32_e32 vcc, v42, v157
	s_and_b64 s[98:99], exec, vcc
	v_max3_f32 v41, v157, v40, v41
	v_sub_f32_e32 v40, v122, v41
	v_exp_f32_e32 v62, v40
	v_sub_f32_e32 v40, v123, v41
	v_exp_f32_e32 v63, v40
	v_sub_f32_e32 v43, v120, v41
	v_exp_f32_e32 v120, v43
	v_sub_f32_e32 v43, v121, v41
	v_exp_f32_e32 v121, v43
	v_sub_f32_e32 v43, v118, v41
	v_add_f32_e32 v42, 0, v62
	v_exp_f32_e32 v118, v43
	v_sub_f32_e32 v43, v119, v41
	v_add_f32_e32 v42, v63, v42
	v_exp_f32_e32 v119, v43
	v_sub_f32_e32 v43, v54, v41
	v_add_f32_e32 v42, v120, v42
	v_exp_f32_e32 v122, v43
	v_sub_f32_e32 v43, v55, v41
	v_add_f32_e32 v42, v121, v42
	v_exp_f32_e32 v55, v43
	v_sub_f32_e32 v43, v116, v41
	v_add_f32_e32 v42, v118, v42
	v_exp_f32_e32 v116, v43
	v_sub_f32_e32 v43, v117, v41
	v_add_f32_e32 v42, v119, v42
	v_exp_f32_e32 v117, v43
	v_sub_f32_e32 v43, v50, v41
	v_add_f32_e32 v42, v122, v42
	v_exp_f32_e32 v123, v43
	v_sub_f32_e32 v43, v51, v41
	v_sub_f32_e32 v40, v157, v41
	v_add_f32_e32 v42, v55, v42
	v_exp_f32_e32 v157, v43
	v_sub_f32_e32 v43, v124, v41
	v_add_f32_e32 v42, v116, v42
	v_exp_f32_e32 v124, v43
	v_sub_f32_e32 v43, v125, v41
	v_add_f32_e32 v42, v117, v42
	v_exp_f32_e32 v125, v43
	v_add_f32_e32 v42, v123, v42
	v_add_f32_e32 v42, v157, v42
	v_add_f32_e32 v42, v124, v42
	v_add_f32_e32 v44, v125, v42
	v_sub_f32_e32 v42, v60, v41
	v_exp_f32_e32 v60, v42
	v_sub_f32_e32 v42, v61, v41
	v_exp_f32_e32 v61, v42
	v_sub_f32_e32 v42, v58, v41
	v_exp_f32_e32 v42, v42
	v_sub_f32_e32 v43, v59, v41
	v_exp_f32_e32 v43, v43
	v_add_f32_e32 v44, v60, v44
	v_add_f32_e32 v44, v61, v44
	v_add_f32_e32 v44, v42, v44
	v_add_f32_e32 v50, v43, v44
	v_sub_f32_e32 v44, v52, v41
	v_exp_f32_e32 v44, v44
	v_sub_f32_e32 v45, v53, v41
	v_exp_f32_e32 v45, v45
	v_sub_f32_e32 v46, v56, v41
	v_exp_f32_e32 v46, v46
	v_sub_f32_e32 v47, v57, v41
	v_exp_f32_e32 v47, v47
	v_add_f32_e32 v50, v44, v50
	v_add_f32_e32 v50, v45, v50
	v_sub_f32_e32 v48, v48, v41
	v_add_f32_e32 v50, v46, v50
	v_exp_f32_e32 v160, v48
	v_sub_f32_e32 v48, v49, v41
	v_add_f32_e32 v159, v47, v50
	v_exp_f32_e32 v161, v48
	ds_read_b64_tr_b16 v[48:49], v152 offset:9216
	ds_read_b64_tr_b16 v[50:51], v152 offset:9472
	ds_read_b64_tr_b16 v[56:57], v152 offset:13312
	ds_read_b64_tr_b16 v[58:59], v152 offset:13568
	v_exp_f32_e32 v40, v40
	v_cvt_pk_bf16_f32 v52, v62, v63
	v_cvt_pk_bf16_f32 v53, v120, v121
	v_cvt_pk_bf16_f32 v54, v118, v119
	v_cvt_pk_bf16_f32 v55, v122, v55
	v_sub_f32_e32 v38, v38, v41
	s_cmp_eq_u64 s[98:99], 0
	s_cbranch_scc1 .Lnr1a
	v_pk_mul_f32 v[14:15], v[14:15], v[40:41] op_sel_hi:[1,0]
	v_pk_mul_f32 v[12:13], v[12:13], v[40:41] op_sel_hi:[1,0]
	v_pk_mul_f32 v[10:11], v[10:11], v[40:41] op_sel_hi:[1,0]
	v_pk_mul_f32 v[8:9], v[8:9], v[40:41] op_sel_hi:[1,0]
	v_pk_mul_f32 v[6:7], v[6:7], v[40:41] op_sel_hi:[1,0]
	v_pk_mul_f32 v[4:5], v[4:5], v[40:41] op_sel_hi:[1,0]
	v_pk_mul_f32 v[2:3], v[2:3], v[40:41] op_sel_hi:[1,0]
	v_pk_mul_f32 v[0:1], v[0:1], v[40:41] op_sel_hi:[1,0]
	v_pk_mul_f32 v[30:31], v[30:31], v[40:41] op_sel_hi:[1,0]
	v_pk_mul_f32 v[28:29], v[28:29], v[40:41] op_sel_hi:[1,0]

; __device__ __forceinline__ unsigned pk_bf16(float lo, float hi) { unsigned r; asm("v_cvt_pk_bf16_f32 %0, %1, %2" : "=v"(r) : "v"(lo), "v"(hi)); return r; }
; __device__ void attn_item(const Params& p, int s_idx, char* smem) {
;     ...
;             float mx = sv[0];
; #pragma unroll
;             for (int i = 1; i < 32; ++i) mx = fmaxf(mx, sv[i]);
;             mx = fmaxf(mx, __shfl_xor(mx, 32));
;             const float mnew = fmaxf(mrun, mx);
;             const float alpha = __builtin_amdgcn_exp2f(mrun - mnew);
;             mrun = mnew;
;             float psum = 0.f;
; #pragma unroll
;             for (int i = 0; i < 32; ++i) { sv[i] = __builtin_amdgcn_exp2f(sv[i] - mnew); psum += sv[i]; }
;             lsum = lsum * alpha + psum;
; #pragma unroll
;             for (int i = 0; i < 16; ++i) { O0[i] *= alpha; O1[i] *= alpha; }
; #pragma unroll
;             for (int g = 0; g < 4; ++g) {
;                 bf16x8 pf;
;                 {
;                     const unsigned u0 = pk_bf16(sv[g * 8 + 0], sv[g * 8 + 1]), u1 = pk_bf16(sv[g * 8 + 2], sv[g * 8 + 3]);
;                     const unsigned u2 = pk_bf16(sv[g * 8 + 4], sv[g * 8 + 5]), u3 = pk_bf16(sv[g * 8 + 6], sv[g * 8 + 7]);
;                     const uint4 uu = {u0, u1, u2, u3};
;                     pf = __builtin_bit_cast(bf16x8, uu);
;                 }
;                 const int koff = (g >> 1) * 32 + (g & 1) * 16 + 8 * hh;
;                 const bf16x8 v0 = *(const bf16x8*)(sVt + ql * 72 + koff);
;                 const bf16x8 v1 = *(const bf16x8*)(sVt + (32 + ql) * 72 + koff);
;                 O0 = __builtin_amdgcn_mfma_f32_32x32x16_bf16(v0, pf, O0, 0, 0, 0);
;                 O1 = __builtin_amdgcn_mfma_f32_32x32x16_bf16(v1, pf, O1, 0, 0, 0);
.LBB0_119:
	s_or_b64 exec, exec, s[42:43]
	v_max_f32_e32 v40, v123, v123
	v_max_f32_e32 v41, v122, v122
	v_max_f32_e32 v40, v41, v40
	v_max3_f32 v40, v40, v120, v121
	v_max3_f32 v40, v40, v118, v119
	v_max3_f32 v40, v40, v54, v55
	v_max3_f32 v40, v40, v116, v117
	v_max3_f32 v40, v40, v50, v51
	v_max3_f32 v40, v40, v124, v125
	v_max3_f32 v40, v40, v60, v61
	v_max3_f32 v40, v40, v58, v59
	v_max3_f32 v40, v40, v52, v53
	v_max3_f32 v40, v40, v56, v57
	v_max3_f32 v40, v40, v48, v49
	v_max3_f32 v40, v40, v38, v39
	v_max3_f32 v40, v40, v34, v35
	v_max3_f32 v40, v40, v36, v37
	v_max3_f32 v40, v40, v32, v33
	v_mov_b32_e32 v41, v40
	s_nop 1
	v_permlane32_swap_b32_e32 v41, v40
	s_waitcnt lgkmcnt(0)
	v_max_f32_e32 v42, v40, v41
	v_add_f32_e32 v43, 0xc3190000, v157
	v_cmp_lt_f32_e32 vcc, v42, v43
	s_andn2_b64 s[98:99], exec, vcc
	s_cbranch_scc0 .LBB0_120
	s_setprio 3
	v_cmp_gt_f32_e32 vcc, v42, v157
	s_and_b64 s[98:99], exec, vcc
	v_max3_f32 v41, v157, v40, v41
	v_sub_f32_e32 v40, v122, v41
	v_exp_f32_e32 v62, v40
	v_sub_f32_e32 v40, v123, v41
	v_exp_f32_e32 v63, v40
	v_sub_f32_e32 v43, v120, v41
	v_exp_f32_e32 v120, v43
	v_sub_f32_e32 v43, v121, v41
	v_exp_f32_e32 v121, v43
	v_sub_f32_e32 v43, v118, v41
	v_add_f32_e32 v42, 0, v62
	v_exp_f32_e32 v118, v43
	v_sub_f32_e32 v43, v119, v41
	v_add_f32_e32 v42, v63, v42
	v_exp_f32_e32 v119, v43
	v_sub_f32_e32 v43, v54, v41
	v_add_f32_e32 v42, v120, v42
	v_exp_f32_e32 v122, v43
	v_sub_f32_e32 v43, v55, v41
	v_add_f32_e32 v42, v121, v42
	v_exp_f32_e32 v55, v43
	v_sub_f32_e32 v43, v116, v41
	v_add_f32_e32 v42, v118, v42
	v_exp_f32_e32 v116, v43
	v_sub_f32_e32 v43, v117, v41
	v_add_f32_e32 v42, v119, v42
	v_exp_f32_e32 v117, v43
	v_sub_f32_e32 v43, v50, v41
	v_add_f32_e32 v42, v122, v42
	v_exp_f32_e32 v123, v43
	v_sub_f32_e32 v43, v51, v41
	v_sub_f32_e32 v40, v157, v41
	v_add_f32_e32 v42, v55, v42
	v_exp_f32_e32 v157, v43
	v_sub_f32_e32 v43, v124, v41
	v_add_f32_e32 v42, v116, v42
	v_exp_f32_e32 v124, v43
	v_sub_f32_e32 v43, v125, v41
	v_add_f32_e32 v42, v117, v42
	v_exp_f32_e32 v125, v43
	v_add_f32_e32 v42, v123, v42
	v_add_f32_e32 v42, v157, v42
	v_add_f32_e32 v42, v124, v42
	v_add_f32_e32 v44, v125, v42
	v_sub_f32_e32 v42, v60, v41
	v_exp_f32_e32 v60, v42
	v_sub_f32_e32 v42, v61, v41
	v_exp_f32_e32 v61, v42
	v_sub_f32_e32 v42, v58, v41
	v_exp_f32_e32 v42, v42
	v_sub_f32_e32 v43, v59, v41
	v_exp_f32_e32 v43, v43
	v_add_f32_e32 v44, v60, v44
	v_add_f32_e32 v44, v61, v44
	v_add_f32_e32 v44, v42, v44
	v_add_f32_e32 v50, v43, v44
	v_sub_f32_e32 v44, v52, v41
	v_exp_f32_e32 v44, v44
	v_sub_f32_e32 v45, v53, v41
	v_exp_f32_e32 v45, v45
	v_sub_f32_e32 v46, v56, v41
	v_exp_f32_e32 v46, v46
	v_sub_f32_e32 v47, v57, v41
	v_exp_f32_e32 v47, v47
	v_add_f32_e32 v50, v44, v50
	v_add_f32_e32 v50, v45, v50
	v_sub_f32_e32 v48, v48, v41
	v_add_f32_e32 v50, v46, v50
	v_exp_f32_e32 v160, v48
	v_sub_f32_e32 v48, v49, v41
	v_add_f32_e32 v159, v47, v50
	v_exp_f32_e32 v161, v48
	ds_read_b64_tr_b16 v[48:49], v152 offset:27904
	ds_read_b64_tr_b16 v[50:51], v152 offset:28160
	ds_read_b64_tr_b16 v[56:57], v152 offset:32000
	ds_read_b64_tr_b16 v[58:59], v152 offset:32256
	v_exp_f32_e32 v40, v40
	v_cvt_pk_bf16_f32 v52, v62, v63
	v_cvt_pk_bf16_f32 v53, v120, v121
	v_cvt_pk_bf16_f32 v54, v118, v119
	v_cvt_pk_bf16_f32 v55, v122, v55
	v_sub_f32_e32 v38, v38, v41
	s_cmp_eq_u64 s[98:99], 0
	s_cbranch_scc1 .Lnr1b
	v_pk_mul_f32 v[14:15], v[14:15], v[40:41] op_sel_hi:[1,0]
	v_pk_mul_f32 v[12:13], v[12:13], v[40:41] op_sel_hi:[1,0]
	v_pk_mul_f32 v[10:11], v[10:11], v[40:41] op_sel_hi:[1,0]
	v_pk_mul_f32 v[8:9], v[8:9], v[40:41] op_sel_hi:[1,0]
	v_pk_mul_f32 v[6:7], v[6:7], v[40:41] op_sel_hi:[1,0]
	v_pk_mul_f32 v[4:5], v[4:5], v[40:41] op_sel_hi:[1,0]
	v_pk_mul_f32 v[2:3], v[2:3], v[40:41] op_sel_hi:[1,0]
	v_pk_mul_f32 v[0:1], v[0:1], v[40:41] op_sel_hi:[1,0]
	v_pk_mul_f32 v[30:31], v[30:31], v[40:41] op_sel_hi:[1,0]
	v_pk_mul_f32 v[28:29], v[28:29], v[40:41] op_sel_hi:[1,0]
